# v19 with the rotated group chosen by XCD parity (whole XCDs start with stick-breaking tasks) instead of alternate workgroups inside each XCD
# baseline (speedup 1.0000x reference)
.LBB0_371:
	s_add_u32 s0, s62, 0x63200000
	s_addc_u32 s1, s63, 0
	s_add_u32 s72, s62, 0x59200000
	s_addc_u32 s73, s63, 0
	v_writelane_b32 v254, s0, 32
	s_cmp_lt_i32 s88, 4
	s_nop 0
	v_writelane_b32 v254, s1, 33
	s_cselect_b64 s[0:1], -1, 0
	s_cmp_gt_i32 s89, 3
	s_cselect_b64 s[2:3], -1, 0
	s_and_b64 s[0:1], s[0:1], s[2:3]
	s_andn2_b64 vcc, exec, s[0:1]
	s_cbranch_vccnz .LBB0_468
	v_writelane_b32 v254, s57, 34
	v_writelane_b32 v254, s56, 35
	v_writelane_b32 v254, s82, 36
	s_cmpk_gt_i32 s87, 0x9ff
	s_nop 0
	v_writelane_b32 v254, s83, 37
	v_writelane_b32 v254, s87, 38
	s_cbranch_scc1 .LBB0_414
	v_and_b32_e32 v1, 32, v0
	v_cmp_eq_u32_e64 s[2:3], 0, v1
	v_lshrrev_b32_e32 v1, 5, v182
	v_lshrrev_b32_e32 v3, 3, v0
	v_and_b32_e32 v3, 2, v3
	v_bfe_u32 v5, v182, 1, 1
	v_lshlrev_b32_e32 v7, 1, v1
	v_lshlrev_b32_e32 v8, 3, v0
	v_bfe_u32 v2, v0, 2, 2
	v_or_b32_e32 v6, v5, v3
	v_and_b32_e32 v8, 8, v8
	v_bitop3_b32 v3, v5, v7, v3 bitop3:0x36
	v_lshlrev_b32_e32 v5, 11, v1
	v_lshl_or_b32 v8, v2, 6, v8
	v_lshl_or_b32 v2, v2, 8, v5
	v_lshl_or_b32 v5, v3, 4, v2
	v_bitop3_b32 v3, v7, v6, 1 bitop3:0x36
	v_lshl_or_b32 v2, v3, 4, v2
	v_lshlrev_b32_e32 v3, 1, v0
	v_lshrrev_b32_e32 v4, 1, v182
	v_and_b32_e32 v3, 8, v3
	v_cmp_gt_u32_e64 s[6:7], 2, v182
	v_readlane_b32 s4, v254, 16
	v_add_u32_e32 v167, v2, v8
	v_lshlrev_b32_e32 v2, 2, v0
	v_and_or_b32 v3, v4, 4, v3
	v_writelane_b32 v254, s6, 39
	s_add_u32 s74, s62, 0x55200000
	v_and_b32_e32 v2, 12, v2
	v_lshrrev_b32_e32 v6, 2, v3
	v_writelane_b32 v254, s7, 40
	s_addc_u32 s75, s63, 0
	s_lshl_b32 s0, s4, 2
	v_and_or_b32 v7, v0, 19, v3
	v_bitop3_b32 v9, v6, v1, v2 bitop3:0x36
	v_lshrrev_b32_e32 v6, 4, v182
	v_readlane_b32 s5, v254, 0
	s_add_i32 s97, s0, 0
	v_lshlrev_b32_e32 v181, 8, v7
	v_and_b32_e32 v7, 15, v0
	v_or_b32_e32 v2, s0, v6
	v_lshlrev_b32_e32 v6, 2, v6
	s_bfe_u32 s0, s5, 0x20006
	v_bitop3_b32 v11, s0, v7, v6 bitop3:0x36
	s_lshl_b32 s0, s4, 10
	v_lshlrev_b32_e32 v4, 3, v1
	s_add_i32 s94, s0, 0
	s_movk_i32 s0, 0x80
	s_movk_i32 s1, 0xc0
	v_and_b32_e32 v165, 31, v0
	v_or_b32_e32 v180, v5, v8
	v_bitop3_b32 v191, v5, 64, v8 bitop3:0x36
	v_bitop3_b32 v193, v5, s0, v8 bitop3:0x36
	v_bitop3_b32 v195, v5, s1, v8 bitop3:0x36
	v_or_b32_e32 v5, 1, v4
	v_cmp_lt_u32_e64 s[12:13], v5, v165
	v_or_b32_e32 v5, 2, v4
	v_cmp_lt_u32_e64 s[14:15], v5, v165
	v_or_b32_e32 v5, 3, v4
	v_cmp_lt_u32_e64 s[16:17], v5, v165
	v_or_b32_e32 v5, 4, v4
	v_cmp_lt_u32_e64 s[18:19], v5, v165
	v_or_b32_e32 v5, 5, v4
	v_cmp_lt_u32_e64 s[20:21], v5, v165
	v_or_b32_e32 v5, 6, v4
	v_cmp_lt_u32_e64 s[22:23], v5, v165
	v_or_b32_e32 v5, 7, v4
	v_cmp_lt_u32_e64 s[24:25], v5, v165
	v_or_b32_e32 v5, 16, v4
	v_cmp_lt_u32_e64 s[26:27], v5, v165
	v_or_b32_e32 v5, 17, v4
	s_add_i32 s97, s97, 0x10000
	v_cmp_lt_u32_e64 s[28:29], v5, v165
	v_or_b32_e32 v5, 18, v4
	v_cmp_lt_u32_e64 s[30:31], v5, v165
	v_or_b32_e32 v5, 19, v4
	s_cmpk_gt_u32 s5, 0x1bf
	v_cmp_lt_u32_e64 s[34:35], v5, v165
	v_or_b32_e32 v5, 20, v4
	s_cselect_b64 s[0:1], -1, 0
	v_cmp_lt_u32_e64 s[36:37], v5, v165
	v_or_b32_e32 v5, 21, v4
	v_writelane_b32 v254, s0, 0
	s_cmp_eq_u32 s4, 7
	v_mov_b32_e32 v3, 0
	v_cmp_lt_u32_e64 s[38:39], v5, v165
	v_or_b32_e32 v5, 22, v4
	v_writelane_b32 v254, s1, 1
	s_cselect_b64 s[82:83], -1, 0
	s_add_i32 s0, s4, -6
	v_lshlrev_b32_e32 v10, 5, v182
	v_lshlrev_b64 v[6:7], 11, v[2:3]
	v_lshlrev_b32_e32 v183, 4, v9
	v_cmp_lt_u32_e64 s[40:41], v5, v165
	v_or_b32_e32 v5, 23, v4
	v_lshlrev_b64 v[8:9], 10, v[2:3]
	v_readlane_b32 s78, v254, 38
	v_writelane_b32 v254, s0, 41
	s_add_i32 s0, s94, 0xc000
	s_mov_b32 s77, 0
	s_waitcnt vmcnt(0)
	v_lshlrev_b32_e32 v164, 3, v11
	v_xor_b32_e32 v184, 32, v183
	v_xor_b32_e32 v185, 64, v183
	v_xor_b32_e32 v186, 0x60, v183
	v_xor_b32_e32 v187, 0x80, v183
	v_xor_b32_e32 v188, 0xa0, v183
	v_xor_b32_e32 v189, 0xc0, v183
	v_xor_b32_e32 v190, 0xe0, v183
	v_cmp_gt_u32_e64 s[6:7], 32, v182
	v_xor_b32_e32 v192, 0x440, v167
	v_xor_b32_e32 v194, 0x480, v167
	v_xor_b32_e32 v196, 0x4c0, v167
	v_cmp_eq_u32_e64 s[8:9], 0, v182
	v_cmp_lt_u32_e64 s[10:11], v4, v165
	v_cmp_lt_u32_e64 s[42:43], v5, v165
	v_add_u32_e32 v197, 0, v181
	v_lshlrev_b32_e32 v166, 2, v1
	s_xor_b32 s95, s78, 15
	s_add_i32 s88, s78, 0xfffffa00
	s_add_i32 s47, s4, -11
	s_add_i32 s92, s4, -7
	v_or_b32_e32 v198, 0xe0, v4
	v_add_u32_e32 v199, s97, v10
	v_lshlrev_b64 v[168:169], 1, v[6:7]
	s_add_i32 s56, s94, 0x2000
	s_add_i32 s57, s94, 0x4000
	s_add_i32 s89, s94, 0x6000
	s_add_i32 s93, s94, 0x8000
	s_add_i32 s68, s94, 0xa000
	v_writelane_b32 v254, s0, 42
	s_add_i32 s0, s94, 0xe000
	s_mov_b32 s5, 0xc3000000
	v_lshlrev_b64 v[170:171], 1, v[8:9]
	s_mov_b32 s80, 0xf149f2ca
	v_mov_b32_e32 v200, 0x80
	v_mov_b32_e32 v201, 0x100
	v_mov_b32_e32 v202, 0x200
	v_mov_b32_e32 v203, 0x400
	v_mov_b32_e32 v204, 0x800
	v_mov_b32_e32 v205, 0x1000
	v_mov_b32_e32 v206, 0x2000
	v_mov_b32_e32 v207, 0x4000
	v_mov_b32_e32 v208, 0x8000
	v_lshlrev_b32_e32 v172, 1, v4
	v_mov_b32_e32 v209, 0xf149f2ca
	v_writelane_b32 v254, s0, 43
	v_writelane_b32 v254, s78, 44
	s_xor_b32 s0, s78, 15
	s_add_i32 s0, s0, s78
	s_nop 0
	v_writelane_b32 v254, s0, 46
	s_and_b32 s0, s78, 1
	s_cmp_eq_u32 s0, 0
	s_cbranch_scc1 .Lp3norot
